# v10 with PV MFMA cluster at priority 2 and QK at 1
# speedup vs baseline: 1.0039x; 1.0039x over previous
; #define SBAR() __builtin_amdgcn_sched_barrier(0)
; template <int DQK, int MODE, bool PIPE>
; DI void attn_core(const u16* __restrict__ Qg, const u16* __restrict__ Kg, const u16* __restrict__ Vtg, int ntiles,
;                   int kr_lo, int rs, int r_q, int c_q, int cs, const float* biasL, char* lds, f32x16 (&o)[4], float& l_out, int tid) {
;     ...
;     for (int i = 0; i < 16; ++i) { p0[i] = __builtin_amdgcn_exp2f(p0[i]); p1[i] = __builtin_amdgcn_exp2f(p1[i]); ps += p0[i] + p1[i]; }
;     l += ps;
;     const char* vb = lds + (t & 1) * A_BUF + A_VOFF + r32 * 136 + h * 8;
;     {
;       bf16x8 pfc;
;       constexpr int R = PV_RING;
;       const unsigned vaddr = (unsigned)(size_t)vb;
;       s16x4 vlo[R], vhi[R];
;       SBAR();
;       vlo[0] = lds_rd64<0>(vaddr); vhi[0] = lds_rd64<16>(vaddr);
;       vlo[1] = lds_rd64<32 * 136>(vaddr); vhi[1] = lds_rd64<32 * 136 + 16>(vaddr);
;       if (R > 2) { vlo[2 % R] = lds_rd64<64 * 136>(vaddr); vhi[2 % R] = lds_rd64<64 * 136 + 16>(vaddr); }
;       if (R > 3) { vlo[3 % R] = lds_rd64<96 * 136>(vaddr); vhi[3 % R] = lds_rd64<96 * 136 + 16>(vaddr); }
;       SBAR();
;       __builtin_amdgcn_s_setprio(1);
;       PvStep<0, 16, R>::run(vaddr, vlo, vhi, p0, p1, pfc, o);
;       __builtin_amdgcn_s_setprio(0);
;     ...
;       if (t + 2 < ntiles) swriteK(t & 1);
;       if (t + 3 < ntiles) gloadK(t + 3);
;     } else {
;       if (is_active(t)) { qk(t, c0, c1); sm_pv(t, c0, c1); }
;       if (t + 1 < ntiles) swriteK((t + 1) & 1);
;       if (t + 2 < ntiles) gloadK(t + 2);
.LBB0_825:
	v_exp_f32_e32 v66, v66
	v_exp_f32_e32 v82, v82
	v_exp_f32_e32 v67, v67
	v_exp_f32_e32 v83, v83
	v_exp_f32_e32 v68, v68
	v_exp_f32_e32 v84, v84
	v_exp_f32_e32 v69, v69
	v_exp_f32_e32 v85, v85
	v_exp_f32_e32 v70, v70
	v_exp_f32_e32 v86, v86
	v_exp_f32_e32 v71, v71
	v_exp_f32_e32 v87, v87
	v_exp_f32_e32 v72, v72
	v_exp_f32_e32 v88, v88
	v_exp_f32_e32 v73, v73
	v_exp_f32_e32 v89, v89
	v_exp_f32_e32 v74, v74
	v_exp_f32_e32 v90, v90
	v_exp_f32_e32 v75, v75
	v_exp_f32_e32 v91, v91
	v_exp_f32_e32 v76, v76
	v_exp_f32_e32 v92, v92
	v_exp_f32_e32 v77, v77
	v_exp_f32_e32 v93, v93
	v_exp_f32_e32 v78, v78
	v_exp_f32_e32 v94, v94
	v_exp_f32_e32 v79, v79
	v_exp_f32_e32 v95, v95
	v_exp_f32_e32 v80, v80
	v_exp_f32_e32 v96, v96
	v_exp_f32_e32 v81, v81
	v_exp_f32_e32 v97, v97
	v_add_u32_e32 v228, s19, v226
	v_add3_u32 v248, v228, v168, s33
	ds_read_b64 v[228:229], v248 offset:0
	ds_read_b64 v[230:231], v248 offset:16
	ds_read_b64 v[232:233], v248 offset:0x1100
	ds_read_b64 v[234:235], v248 offset:0x1110
	ds_read_b64 v[236:237], v248 offset:0x2200
	ds_read_b64 v[238:239], v248 offset:0x2210
	ds_read_b64 v[240:241], v248 offset:0x3300
	ds_read_b64 v[242:243], v248 offset:0x3310
	s_setprio 2
	s_waitcnt lgkmcnt(4)
	v_cvt_pk_bf16_f32 v244, v66, v67
	v_cvt_pk_bf16_f32 v245, v68, v69
	v_cvt_pk_bf16_f32 v246, v70, v71
	v_cvt_pk_bf16_f32 v247, v72, v73
	s_nop 1
	v_mfma_f32_32x32x16_bf16 v[50:65], v[228:231], v[244:247], v[50:65]
	ds_read_b64 v[228:229], v248 offset:32
	ds_read_b64 v[230:231], v248 offset:48
	v_mfma_f32_32x32x16_bf16 v[34:49], v[232:235], v[244:247], v[34:49]
	ds_read_b64 v[232:233], v248 offset:0x1120
	ds_read_b64 v[234:235], v248 offset:0x1130
	s_waitcnt lgkmcnt(4)
	v_mfma_f32_32x32x16_bf16 v[18:33], v[236:239], v[244:247], v[18:33]
	ds_read_b64 v[236:237], v248 offset:0x2220
	ds_read_b64 v[238:239], v248 offset:0x2230
	v_mfma_f32_32x32x16_bf16 v[2:17], v[240:243], v[244:247], v[2:17]
	ds_read_b64 v[240:241], v248 offset:0x3320
	ds_read_b64 v[242:243], v248 offset:0x3330
	s_waitcnt lgkmcnt(4)
	v_cvt_pk_bf16_f32 v244, v74, v75
	v_cvt_pk_bf16_f32 v245, v76, v77
	v_cvt_pk_bf16_f32 v246, v78, v79
	v_cvt_pk_bf16_f32 v247, v80, v81
	s_nop 1
	v_mfma_f32_32x32x16_bf16 v[50:65], v[228:231], v[244:247], v[50:65]
	ds_read_b64 v[228:229], v248 offset:64
	ds_read_b64 v[230:231], v248 offset:0x50
	v_mfma_f32_32x32x16_bf16 v[34:49], v[232:235], v[244:247], v[34:49]
	ds_read_b64 v[232:233], v248 offset:0x1140
	ds_read_b64 v[234:235], v248 offset:0x1150
	s_waitcnt lgkmcnt(4)
	v_mfma_f32_32x32x16_bf16 v[18:33], v[236:239], v[244:247], v[18:33]
	ds_read_b64 v[236:237], v248 offset:0x2240
	ds_read_b64 v[238:239], v248 offset:0x2250
	v_mfma_f32_32x32x16_bf16 v[2:17], v[240:243], v[244:247], v[2:17]
	ds_read_b64 v[240:241], v248 offset:0x3340
	ds_read_b64 v[242:243], v248 offset:0x3350
	s_waitcnt lgkmcnt(4)
	v_cvt_pk_bf16_f32 v244, v82, v83
	v_cvt_pk_bf16_f32 v245, v84, v85
	v_cvt_pk_bf16_f32 v246, v86, v87
	v_cvt_pk_bf16_f32 v247, v88, v89
	s_nop 1
	v_mfma_f32_32x32x16_bf16 v[50:65], v[228:231], v[244:247], v[50:65]
	ds_read_b64 v[228:229], v248 offset:0x60
	ds_read_b64 v[230:231], v248 offset:0x70
	v_mfma_f32_32x32x16_bf16 v[34:49], v[232:235], v[244:247], v[34:49]
	ds_read_b64 v[232:233], v248 offset:0x1160
	ds_read_b64 v[234:235], v248 offset:0x1170
	s_waitcnt lgkmcnt(4)
	v_mfma_f32_32x32x16_bf16 v[18:33], v[236:239], v[244:247], v[18:33]
	ds_read_b64 v[236:237], v248 offset:0x2260
	ds_read_b64 v[238:239], v248 offset:0x2270
	v_mfma_f32_32x32x16_bf16 v[2:17], v[240:243], v[244:247], v[2:17]
	ds_read_b64 v[240:241], v248 offset:0x3360
	ds_read_b64 v[242:243], v248 offset:0x3370
	s_waitcnt lgkmcnt(4)
	v_cvt_pk_bf16_f32 v244, v90, v91
	v_cvt_pk_bf16_f32 v245, v92, v93
	v_cvt_pk_bf16_f32 v246, v94, v95
	v_cvt_pk_bf16_f32 v247, v96, v97
	s_nop 1
	v_mfma_f32_32x32x16_bf16 v[50:65], v[228:231], v[244:247], v[50:65]
	v_mfma_f32_32x32x16_bf16 v[34:49], v[232:235], v[244:247], v[34:49]
	s_waitcnt lgkmcnt(0)
	v_mfma_f32_32x32x16_bf16 v[18:33], v[236:239], v[244:247], v[18:33]
	v_mfma_f32_32x32x16_bf16 v[2:17], v[240:243], v[244:247], v[2:17]
	s_setprio 0
	s_andn2_b64 vcc, exec, s[10:11]
	s_cbranch_vccnz .LBB0_827
	s_bitcmp1_b32 s18, 0
	s_cselect_b32 s6, 0xa800, 0
	v_add3_u32 v228, s6, v167, v169
	v_add3_u32 v229, s6, v199, v217
	v_add3_u32 v230, s6, v220, v221
	s_waitcnt vmcnt(2)
	ds_write_b128 v228, v[146:149]
	s_waitcnt vmcnt(1)
	ds_write_b128 v229, v[154:157]
	s_waitcnt vmcnt(0)
	ds_write_b128 v230, v[162:165]

; #define SBAR() __builtin_amdgcn_sched_barrier(0)
; template <int DQK, int MODE, bool PIPE>
; DI void attn_core(const u16* __restrict__ Qg, const u16* __restrict__ Kg, const u16* __restrict__ Vtg, int ntiles,
;                   int kr_lo, int rs, int r_q, int c_q, int cs, const float* biasL, char* lds, f32x16 (&o)[4], float& l_out, int tid) {
;     ...
;     for (int i = 0; i < 16; ++i) { p0[i] = __builtin_amdgcn_exp2f(p0[i]); p1[i] = __builtin_amdgcn_exp2f(p1[i]); ps += p0[i] + p1[i]; }
;     l += ps;
;     const char* vb = lds + (t & 1) * A_BUF + A_VOFF + r32 * 136 + h * 8;
;     {
;       bf16x8 pfc;
;       constexpr int R = PV_RING;
;       const unsigned vaddr = (unsigned)(size_t)vb;
;       s16x4 vlo[R], vhi[R];
;       SBAR();
;       vlo[0] = lds_rd64<0>(vaddr); vhi[0] = lds_rd64<16>(vaddr);
;       vlo[1] = lds_rd64<32 * 136>(vaddr); vhi[1] = lds_rd64<32 * 136 + 16>(vaddr);
;       if (R > 2) { vlo[2 % R] = lds_rd64<64 * 136>(vaddr); vhi[2 % R] = lds_rd64<64 * 136 + 16>(vaddr); }
;       if (R > 3) { vlo[3 % R] = lds_rd64<96 * 136>(vaddr); vhi[3 % R] = lds_rd64<96 * 136 + 16>(vaddr); }
;       SBAR();
;       __builtin_amdgcn_s_setprio(1);
;       PvStep<0, 16, R>::run(vaddr, vlo, vhi, p0, p1, pfc, o);
;       __builtin_amdgcn_s_setprio(0);
;     ...
;       if (t + 2 < ntiles) swriteK(t & 1);
;       if (t + 3 < ntiles) gloadK(t + 3);
;     } else {
;       if (is_active(t)) { qk(t, c0, c1); sm_pv(t, c0, c1); }
;       if (t + 1 < ntiles) swriteK((t + 1) & 1);
;       if (t + 2 < ntiles) gloadK(t + 2);
.LBB0_844:
	v_exp_f32_e32 v82, v82
	v_exp_f32_e32 v98, v98
	v_exp_f32_e32 v83, v83
	v_exp_f32_e32 v99, v99
	v_exp_f32_e32 v84, v84
	v_exp_f32_e32 v100, v100
	v_exp_f32_e32 v85, v85
	v_exp_f32_e32 v101, v101
	v_exp_f32_e32 v86, v86
	v_exp_f32_e32 v102, v102
	v_exp_f32_e32 v87, v87
	v_exp_f32_e32 v103, v103
	v_exp_f32_e32 v88, v88
	v_exp_f32_e32 v104, v104
	v_exp_f32_e32 v89, v89
	v_exp_f32_e32 v105, v105
	v_exp_f32_e32 v90, v90
	v_exp_f32_e32 v106, v106
	v_exp_f32_e32 v91, v91
	v_exp_f32_e32 v107, v107
	v_exp_f32_e32 v92, v92
	v_exp_f32_e32 v108, v108
	v_exp_f32_e32 v93, v93
	v_exp_f32_e32 v109, v109
	v_exp_f32_e32 v94, v94
	v_exp_f32_e32 v110, v110
	v_exp_f32_e32 v95, v95
	v_exp_f32_e32 v111, v111
	v_exp_f32_e32 v96, v96
	v_exp_f32_e32 v112, v112
	v_exp_f32_e32 v97, v97
	v_exp_f32_e32 v113, v113
	v_add_u32_e32 v177, s15, v168
	v_add3_u32 v177, v177, v166, s33
	ds_read_b64 v[216:217], v177 offset:0
	ds_read_b64 v[218:219], v177 offset:16
	ds_read_b64 v[220:221], v177 offset:0x1100
	ds_read_b64 v[222:223], v177 offset:0x1110
	ds_read_b64 v[224:225], v177 offset:0x2200
	ds_read_b64 v[226:227], v177 offset:0x2210
	ds_read_b64 v[228:229], v177 offset:0x3300
	ds_read_b64 v[230:231], v177 offset:0x3310
	s_setprio 2
	s_waitcnt lgkmcnt(4)
	v_cvt_pk_bf16_f32 v232, v82, v83
	v_cvt_pk_bf16_f32 v233, v84, v85
	v_cvt_pk_bf16_f32 v234, v86, v87
	v_cvt_pk_bf16_f32 v235, v88, v89
	s_nop 1
	v_mfma_f32_32x32x16_bf16 v[66:81], v[216:219], v[232:235], v[66:81]
	ds_read_b64 v[216:217], v177 offset:32
	ds_read_b64 v[218:219], v177 offset:48
	v_mfma_f32_32x32x16_bf16 v[50:65], v[220:223], v[232:235], v[50:65]
	ds_read_b64 v[220:221], v177 offset:0x1120
	ds_read_b64 v[222:223], v177 offset:0x1130
	s_waitcnt lgkmcnt(4)
	v_mfma_f32_32x32x16_bf16 v[34:49], v[224:227], v[232:235], v[34:49]
	ds_read_b64 v[224:225], v177 offset:0x2220
	ds_read_b64 v[226:227], v177 offset:0x2230
	v_mfma_f32_32x32x16_bf16 v[2:17], v[228:231], v[232:235], v[2:17]
	ds_read_b64 v[228:229], v177 offset:0x3320
	ds_read_b64 v[230:231], v177 offset:0x3330
	s_waitcnt lgkmcnt(4)
	v_cvt_pk_bf16_f32 v232, v90, v91
	v_cvt_pk_bf16_f32 v233, v92, v93
	v_cvt_pk_bf16_f32 v234, v94, v95
	v_cvt_pk_bf16_f32 v235, v96, v97
	s_nop 1
	v_mfma_f32_32x32x16_bf16 v[66:81], v[216:219], v[232:235], v[66:81]
	ds_read_b64 v[216:217], v177 offset:64
	ds_read_b64 v[218:219], v177 offset:0x50
	v_mfma_f32_32x32x16_bf16 v[50:65], v[220:223], v[232:235], v[50:65]
	ds_read_b64 v[220:221], v177 offset:0x1140
	ds_read_b64 v[222:223], v177 offset:0x1150
	s_waitcnt lgkmcnt(4)
	v_mfma_f32_32x32x16_bf16 v[34:49], v[224:227], v[232:235], v[34:49]
	ds_read_b64 v[224:225], v177 offset:0x2240
	ds_read_b64 v[226:227], v177 offset:0x2250
	v_mfma_f32_32x32x16_bf16 v[2:17], v[228:231], v[232:235], v[2:17]
	ds_read_b64 v[228:229], v177 offset:0x3340
	ds_read_b64 v[230:231], v177 offset:0x3350
	s_waitcnt lgkmcnt(4)
	v_cvt_pk_bf16_f32 v232, v98, v99
	v_cvt_pk_bf16_f32 v233, v100, v101
	v_cvt_pk_bf16_f32 v234, v102, v103
	v_cvt_pk_bf16_f32 v235, v104, v105
	s_nop 1
	v_mfma_f32_32x32x16_bf16 v[66:81], v[216:219], v[232:235], v[66:81]
	ds_read_b64 v[216:217], v177 offset:0x60
	ds_read_b64 v[218:219], v177 offset:0x70
	v_mfma_f32_32x32x16_bf16 v[50:65], v[220:223], v[232:235], v[50:65]
	ds_read_b64 v[220:221], v177 offset:0x1160
	ds_read_b64 v[222:223], v177 offset:0x1170
	s_waitcnt lgkmcnt(4)
	v_mfma_f32_32x32x16_bf16 v[34:49], v[224:227], v[232:235], v[34:49]
	ds_read_b64 v[224:225], v177 offset:0x2260
	ds_read_b64 v[226:227], v177 offset:0x2270
	v_mfma_f32_32x32x16_bf16 v[2:17], v[228:231], v[232:235], v[2:17]
	ds_read_b64 v[228:229], v177 offset:0x3360
	ds_read_b64 v[230:231], v177 offset:0x3370
	s_waitcnt lgkmcnt(4)
	v_cvt_pk_bf16_f32 v232, v106, v107
	v_cvt_pk_bf16_f32 v233, v108, v109
	v_cvt_pk_bf16_f32 v234, v110, v111
	v_cvt_pk_bf16_f32 v235, v112, v113
	s_nop 1
	v_mfma_f32_32x32x16_bf16 v[66:81], v[216:219], v[232:235], v[66:81]
	v_mfma_f32_32x32x16_bf16 v[50:65], v[220:223], v[232:235], v[50:65]
	s_waitcnt lgkmcnt(0)
	v_mfma_f32_32x32x16_bf16 v[34:49], v[224:227], v[232:235], v[34:49]
	v_mfma_f32_32x32x16_bf16 v[2:17], v[228:231], v[232:235], v[2:17]
	s_setprio 0
	s_andn2_b64 vcc, exec, s[0:1]
	s_cbranch_vccnz .LBB0_846
	s_bitcmp1_b32 s14, 0
	s_cselect_b32 s0, 0xa800, 0
	v_add_u32_e32 v177, s0, v143
	s_waitcnt vmcnt(0)
	ds_write_b128 v177, v[138:141]

; #define SBAR() __builtin_amdgcn_sched_barrier(0)
; template <int DQK, int MODE, bool PIPE>
; DI void attn_core(const u16* __restrict__ Qg, const u16* __restrict__ Kg, const u16* __restrict__ Vtg, int ntiles,
;                   int kr_lo, int rs, int r_q, int c_q, int cs, const float* biasL, char* lds, f32x16 (&o)[4], float& l_out, int tid) {
;     ...
;     for (int i = 0; i < 16; ++i) { p0[i] = __builtin_amdgcn_exp2f(p0[i]); p1[i] = __builtin_amdgcn_exp2f(p1[i]); ps += p0[i] + p1[i]; }
;     l += ps;
;     const char* vb = lds + (t & 1) * A_BUF + A_VOFF + r32 * 136 + h * 8;
;     {
;       bf16x8 pfc;
;       constexpr int R = PV_RING;
;       const unsigned vaddr = (unsigned)(size_t)vb;
;       s16x4 vlo[R], vhi[R];
;       SBAR();
;       vlo[0] = lds_rd64<0>(vaddr); vhi[0] = lds_rd64<16>(vaddr);
;       vlo[1] = lds_rd64<32 * 136>(vaddr); vhi[1] = lds_rd64<32 * 136 + 16>(vaddr);
;       if (R > 2) { vlo[2 % R] = lds_rd64<64 * 136>(vaddr); vhi[2 % R] = lds_rd64<64 * 136 + 16>(vaddr); }
;       if (R > 3) { vlo[3 % R] = lds_rd64<96 * 136>(vaddr); vhi[3 % R] = lds_rd64<96 * 136 + 16>(vaddr); }
;       SBAR();
;       __builtin_amdgcn_s_setprio(1);
;       PvStep<0, 16, R>::run(vaddr, vlo, vhi, p0, p1, pfc, o);
;       __builtin_amdgcn_s_setprio(0);
;     ...
;       if (t + 2 < ntiles) swriteK(t & 1);
;       if (t + 3 < ntiles) gloadK(t + 3);
;     } else {
;       if (is_active(t)) { qk(t, c0, c1); sm_pv(t, c0, c1); }
;       if (t + 1 < ntiles) swriteK((t + 1) & 1);
;       if (t + 2 < ntiles) gloadK(t + 2);
.LBB0_860:
	v_exp_f32_e32 v82, v82
	v_exp_f32_e32 v98, v98
	v_exp_f32_e32 v83, v83
	v_exp_f32_e32 v99, v99
	v_exp_f32_e32 v84, v84
	v_exp_f32_e32 v100, v100
	v_exp_f32_e32 v85, v85
	v_exp_f32_e32 v101, v101
	v_exp_f32_e32 v86, v86
	v_exp_f32_e32 v102, v102
	v_exp_f32_e32 v87, v87
	v_exp_f32_e32 v103, v103
	v_exp_f32_e32 v88, v88
	v_exp_f32_e32 v104, v104
	v_exp_f32_e32 v89, v89
	v_exp_f32_e32 v105, v105
	v_exp_f32_e32 v90, v90
	v_exp_f32_e32 v106, v106
	v_exp_f32_e32 v91, v91
	v_exp_f32_e32 v107, v107
	v_exp_f32_e32 v92, v92
	v_exp_f32_e32 v108, v108
	v_exp_f32_e32 v93, v93
	v_exp_f32_e32 v109, v109
	v_exp_f32_e32 v94, v94
	v_exp_f32_e32 v110, v110
	v_exp_f32_e32 v95, v95
	v_exp_f32_e32 v111, v111
	v_exp_f32_e32 v96, v96
	v_exp_f32_e32 v112, v112
	v_exp_f32_e32 v97, v97
	v_exp_f32_e32 v113, v113
	v_add_u32_e32 v156, s12, v168
	v_add3_u32 v160, v156, v166, s33
	ds_read_b64 v[156:157], v160 offset:0
	ds_read_b64 v[158:159], v160 offset:16
	ds_read_b64 v[170:171], v160 offset:0x1100
	ds_read_b64 v[172:173], v160 offset:0x1110
	ds_read_b64 v[174:175], v160 offset:0x2200
	ds_read_b64 v[176:177], v160 offset:0x2210
	ds_read_b64 v[216:217], v160 offset:0x3300
	ds_read_b64 v[218:219], v160 offset:0x3310
	s_setprio 2
	s_waitcnt lgkmcnt(4)
	v_cvt_pk_bf16_f32 v220, v82, v83
	v_cvt_pk_bf16_f32 v221, v84, v85
	v_cvt_pk_bf16_f32 v222, v86, v87
	v_cvt_pk_bf16_f32 v223, v88, v89
	s_nop 1
	v_mfma_f32_32x32x16_bf16 v[66:81], v[156:159], v[220:223], v[66:81]
	ds_read_b64 v[156:157], v160 offset:32
	ds_read_b64 v[158:159], v160 offset:48
	v_mfma_f32_32x32x16_bf16 v[50:65], v[170:173], v[220:223], v[50:65]
	ds_read_b64 v[170:171], v160 offset:0x1120
	ds_read_b64 v[172:173], v160 offset:0x1130
	s_waitcnt lgkmcnt(4)
	v_mfma_f32_32x32x16_bf16 v[18:33], v[174:177], v[220:223], v[18:33]
	ds_read_b64 v[174:175], v160 offset:0x2220
	ds_read_b64 v[176:177], v160 offset:0x2230
	v_mfma_f32_32x32x16_bf16 v[2:17], v[216:219], v[220:223], v[2:17]
	ds_read_b64 v[216:217], v160 offset:0x3320
	ds_read_b64 v[218:219], v160 offset:0x3330
	s_waitcnt lgkmcnt(4)
	v_cvt_pk_bf16_f32 v220, v90, v91
	v_cvt_pk_bf16_f32 v221, v92, v93
	v_cvt_pk_bf16_f32 v222, v94, v95
	v_cvt_pk_bf16_f32 v223, v96, v97
	s_nop 1
	v_mfma_f32_32x32x16_bf16 v[66:81], v[156:159], v[220:223], v[66:81]
	ds_read_b64 v[156:157], v160 offset:64
	ds_read_b64 v[158:159], v160 offset:0x50
	v_mfma_f32_32x32x16_bf16 v[50:65], v[170:173], v[220:223], v[50:65]
	ds_read_b64 v[170:171], v160 offset:0x1140
	ds_read_b64 v[172:173], v160 offset:0x1150
	s_waitcnt lgkmcnt(4)
	v_mfma_f32_32x32x16_bf16 v[18:33], v[174:177], v[220:223], v[18:33]
	ds_read_b64 v[174:175], v160 offset:0x2240
	ds_read_b64 v[176:177], v160 offset:0x2250
	v_mfma_f32_32x32x16_bf16 v[2:17], v[216:219], v[220:223], v[2:17]
	ds_read_b64 v[216:217], v160 offset:0x3340
	ds_read_b64 v[218:219], v160 offset:0x3350
	s_waitcnt lgkmcnt(4)
	v_cvt_pk_bf16_f32 v220, v98, v99
	v_cvt_pk_bf16_f32 v221, v100, v101
	v_cvt_pk_bf16_f32 v222, v102, v103
	v_cvt_pk_bf16_f32 v223, v104, v105
	s_nop 1
	v_mfma_f32_32x32x16_bf16 v[66:81], v[156:159], v[220:223], v[66:81]
	ds_read_b64 v[156:157], v160 offset:0x60
	ds_read_b64 v[158:159], v160 offset:0x70
	v_mfma_f32_32x32x16_bf16 v[50:65], v[170:173], v[220:223], v[50:65]
	ds_read_b64 v[170:171], v160 offset:0x1160
	ds_read_b64 v[172:173], v160 offset:0x1170
	s_waitcnt lgkmcnt(4)
	v_mfma_f32_32x32x16_bf16 v[18:33], v[174:177], v[220:223], v[18:33]
	ds_read_b64 v[174:175], v160 offset:0x2260
	ds_read_b64 v[176:177], v160 offset:0x2270
	v_mfma_f32_32x32x16_bf16 v[2:17], v[216:219], v[220:223], v[2:17]
	ds_read_b64 v[216:217], v160 offset:0x3360
	ds_read_b64 v[218:219], v160 offset:0x3370
	s_waitcnt lgkmcnt(4)
	v_cvt_pk_bf16_f32 v220, v106, v107
	v_cvt_pk_bf16_f32 v221, v108, v109
	v_cvt_pk_bf16_f32 v222, v110, v111
	v_cvt_pk_bf16_f32 v223, v112, v113
	s_nop 1
	v_mfma_f32_32x32x16_bf16 v[66:81], v[156:159], v[220:223], v[66:81]
	v_mfma_f32_32x32x16_bf16 v[50:65], v[170:173], v[220:223], v[50:65]
	s_waitcnt lgkmcnt(0)
	v_mfma_f32_32x32x16_bf16 v[18:33], v[174:177], v[220:223], v[18:33]
	v_mfma_f32_32x32x16_bf16 v[2:17], v[216:219], v[220:223], v[2:17]
	s_setprio 0
	s_andn2_b64 vcc, exec, s[0:1]
	s_cbranch_vccnz .LBB0_862
	s_bitcmp1_b32 s11, 0
	s_cselect_b32 s0, 0xa800, 0
	v_add_u32_e32 v156, s0, v143
	s_waitcnt vmcnt(0)
	ds_write_b128 v156, v[138:141]
